# + gla_prep cumulative-decay LDS fixup batched (32 reads in flight)
# baseline (speedup 1.0000x reference)
; #define LAS __attribute__((address_space(3)))
; __device__ __forceinline__ void phase_gla_prep(KArgs a, LAS unsigned char* lds, int tid, int wave, int lane) {
;     ...
;             for (int t = 0; t < 32; ++t) { const int tt = hf * 32 + t; float z = bgk;
; #pragma unroll
;                 for (int r4 = 0; r4 < 4; ++r4) { const f32x4 gv = *(const LAS f32x4*)(g1s + tt * 16 + r4 * 4); z += gv[0] * w2[r4 * 4] + gv[1] * w2[r4 * 4 + 1] + gv[2] * w2[r4 * 4 + 2] + gv[3] * w2[r4 * 4 + 3]; }
;                 const float ls = fminf(z, 0.f) - log1pf(__expf(-fabsf(z)));
;                 cum += ls * 0.0625f; BC[tt * BC_LD + k] = cum; }
.LBB0_826:
	v_add_u32_e32 v80, 0, v44
	v_add_u32_e32 v70, 0x20c00, v80
	v_add_u32_e32 v74, 0x20c10, v80
	ds_read_b128 v[70:73], v70
	ds_read_b128 v[74:77], v74
	s_add_i32 s75, s75, -1
	v_add_u32_e32 v44, 64, v44
	s_cmp_eq_u32 s75, 0
	s_waitcnt lgkmcnt(1)
	v_mov_b32_e32 v78, v70
	s_waitcnt lgkmcnt(0)
	v_mov_b32_e32 v79, v74
	v_mov_b32_e32 v74, v71
	s_waitcnt vmcnt(11)
	v_pk_mul_f32 v[70:71], v[4:5], v[74:75]
	v_mov_b32_e32 v74, v72
	v_pk_fma_f32 v[70:71], v[2:3], v[78:79], v[70:71]
	v_mov_b32_e32 v75, v76
	s_waitcnt vmcnt(10)
	v_pk_fma_f32 v[70:71], v[6:7], v[74:75], v[70:71]
	v_mov_b32_e32 v76, v73
	s_waitcnt vmcnt(9)
	v_pk_fma_f32 v[70:71], v[8:9], v[76:77], v[70:71]
	v_add_u32_e32 v74, 0x20c30, v80
	s_waitcnt vmcnt(0)
	v_add_f32_e32 v70, v42, v70
	v_add_f32_e32 v81, v70, v71
	v_add_u32_e32 v70, 0x20c20, v80
	ds_read_b128 v[70:73], v70
	ds_read_b128 v[74:77], v74
	s_waitcnt lgkmcnt(1)
	v_mov_b32_e32 v78, v70
	s_waitcnt lgkmcnt(0)
	v_mov_b32_e32 v79, v74
	v_mov_b32_e32 v74, v71
	v_pk_mul_f32 v[70:71], v[12:13], v[74:75]
	v_mov_b32_e32 v74, v72
	v_pk_fma_f32 v[70:71], v[10:11], v[78:79], v[70:71]
	v_mov_b32_e32 v75, v76
	v_pk_fma_f32 v[70:71], v[14:15], v[74:75], v[70:71]
	v_mov_b32_e32 v76, v73
	v_pk_fma_f32 v[70:71], v[16:17], v[76:77], v[70:71]
	s_nop 0
	v_add_f32_e32 v70, v81, v70
	v_add_f32_e32 v70, v70, v71
	v_min_f32_e32 v84, 0, v70
	v_mul_f32_e64 v70, |v70|, s60
	v_exp_f32_e32 v85, v70
	s_nop 0
	v_add_f32_e32 v72, 1.0, v85
	v_add_f32_e32 v70, -1.0, v72
	v_sub_f32_e32 v71, v70, v72
	v_add_f32_e32 v71, 1.0, v71
	v_sub_f32_e32 v70, v85, v70
	v_add_f32_e32 v73, v70, v71
	v_frexp_mant_f32_e32 v70, v72
	v_cmp_gt_f32_e32 vcc, s3, v70
	v_cvt_f64_f32_e32 v[70:71], v72
	v_frexp_exp_i32_f64_e32 v70, v[70:71]
	v_subbrev_co_u32_e32 v78, vcc, 0, v70, vcc
	v_sub_u32_e32 v70, 0, v78
	v_ldexp_f32 v71, v72, v70
	v_add_f32_e32 v72, -1.0, v71
	v_add_f32_e32 v74, 1.0, v71
	v_ldexp_f32 v70, v73, v70
	v_add_f32_e32 v73, 1.0, v72
	v_add_f32_e32 v75, -1.0, v74
	v_sub_f32_e32 v73, v71, v73
	v_sub_f32_e32 v71, v71, v75
	v_add_f32_e32 v73, v70, v73
	v_add_f32_e32 v70, v70, v71
	v_add_f32_e32 v79, v74, v70
	v_rcp_f32_e32 v81, v79
	v_sub_f32_e32 v71, v79, v74
	v_sub_f32_e32 v80, v70, v71
	v_add_f32_e32 v71, v72, v73
	v_mul_f32_e32 v83, v71, v81
	v_sub_f32_e32 v70, v71, v72
	v_mul_f32_e32 v72, v79, v83
	v_fma_f32 v74, v83, v79, -v72
	v_fmac_f32_e32 v74, v83, v80
	v_sub_f32_e32 v82, v73, v70
	v_add_f32_e32 v70, v72, v74
	v_sub_f32_e32 v73, v71, v70
	v_pk_add_f32 v[76:77], v[70:71], v[72:73] neg_lo:[0,1] neg_hi:[0,1]
	v_mov_b32_e32 v75, v70
	v_pk_add_f32 v[70:71], v[76:77], v[74:75] neg_lo:[0,1] neg_hi:[0,1]
	v_cmp_neq_f32_e32 vcc, s34, v85
	v_add_f32_e32 v71, v82, v71
	v_add_f32_e32 v70, v70, v71
	v_add_f32_e32 v71, v73, v70
	v_mul_f32_e32 v82, v81, v71
	v_mul_f32_e32 v72, v79, v82
	v_fma_f32 v74, v82, v79, -v72
	v_fmac_f32_e32 v74, v82, v80
	v_sub_f32_e32 v73, v73, v71
	v_add_f32_e32 v79, v70, v73
	v_add_f32_e32 v70, v72, v74
	v_sub_f32_e32 v73, v71, v70
	v_pk_add_f32 v[76:77], v[70:71], v[72:73] neg_lo:[0,1] neg_hi:[0,1]
	v_mov_b32_e32 v75, v70
	v_pk_add_f32 v[70:71], v[76:77], v[74:75] neg_lo:[0,1] neg_hi:[0,1]
	s_nop 0
	v_add_f32_e32 v71, v79, v71
	v_add_f32_e32 v70, v70, v71
	v_add_f32_e32 v71, v83, v82
	v_add_f32_e32 v70, v73, v70
	v_sub_f32_e32 v72, v71, v83
	v_mul_f32_e32 v70, v81, v70
	v_sub_f32_e32 v72, v82, v72
	v_add_f32_e32 v72, v72, v70
	v_add_f32_e32 v74, v71, v72
	v_mul_f32_e32 v75, v74, v74
	v_fmamk_f32 v70, v75, 0x3e9b6dac, v226
	v_fmaak_f32 v189, v75, v70, 0x3f2aaada
	v_cvt_f32_i32_e32 v70, v78
	v_sub_f32_e32 v71, v74, v71
	v_sub_f32_e32 v71, v72, v71
	v_ldexp_f32 v76, v71, 1
	v_mul_f32_e32 v71, v74, v75
	v_ldexp_f32 v73, v74, 1
	v_pk_mul_f32 v[74:75], v[70:71], v[188:189]
	s_nop 0
	v_fma_f32 v72, v70, s80, -v74
	v_fmac_f32_e32 v72, 0xb102e308, v70
	v_pk_add_f32 v[70:71], v[74:75], v[72:73]
	s_nop 0
	v_sub_f32_e32 v73, v71, v73
	v_sub_f32_e32 v73, v75, v73
	v_add_f32_e32 v77, v76, v73
	v_mov_b32_e32 v76, v74
	v_pk_add_f32 v[74:75], v[70:71], v[74:75] neg_lo:[0,1] neg_hi:[0,1]
	v_pk_add_f32 v[78:79], v[70:71], v[76:77]
	v_mov_b32_e32 v73, v70
	v_mov_b32_e32 v75, v79
	v_pk_add_f32 v[80:81], v[72:73], v[74:75] neg_lo:[0,1] neg_hi:[0,1]
	v_pk_add_f32 v[72:73], v[72:73], v[74:75]
	v_mov_b32_e32 v76, v77
	v_pk_add_f32 v[74:75], v[72:73], v[70:71] op_sel:[1,0] op_sel_hi:[0,1] neg_lo:[0,1] neg_hi:[0,1]
	v_pk_add_f32 v[82:83], v[78:79], v[74:75] op_sel_hi:[1,0] neg_lo:[0,1] neg_hi:[0,1]
	v_mov_b32_e32 v78, v79
	v_mov_b32_e32 v79, v73
	v_pk_mov_b32 v[74:75], v[70:71], v[74:75] op_sel:[1,0]
	v_mov_b32_e32 v77, v70
	v_pk_add_f32 v[74:75], v[78:79], v[74:75] neg_lo:[0,1] neg_hi:[0,1]
	v_mov_b32_e32 v82, v80
	v_pk_add_f32 v[70:71], v[76:77], v[74:75] neg_lo:[0,1] neg_hi:[0,1]
	v_mov_b32_e32 v81, v73
	v_pk_add_f32 v[74:75], v[82:83], v[70:71]
	s_nop 0
	v_pk_add_f32 v[76:77], v[74:75], v[74:75] op_sel:[0,1] op_sel_hi:[1,0]
	s_nop 0
	v_pk_add_f32 v[72:73], v[72:73], v[76:77] op_sel:[1,0] op_sel_hi:[0,1]
	v_mov_b32_e32 v75, v72
	v_pk_add_f32 v[78:79], v[74:75], v[80:81] neg_lo:[0,1] neg_hi:[0,1]
	v_mov_b32_e32 v71, v76
	v_sub_f32_e32 v73, v74, v78
	v_pk_add_f32 v[70:71], v[70:71], v[78:79] neg_lo:[0,1] neg_hi:[0,1]
	v_sub_f32_e32 v73, v80, v73
	v_add_f32_e32 v70, v70, v73
	v_add_f32_e32 v70, v70, v71
	v_add_f32_e32 v70, v72, v70
	v_cndmask_b32_e32 v70, v228, v70, vcc
	v_cmp_ngt_f32_e32 vcc, -1.0, v85
	s_nop 1
	v_cndmask_b32_e32 v70, v229, v70, vcc
	v_cmp_neq_f32_e32 vcc, -1.0, v85
	s_nop 1
	v_cndmask_b32_e32 v70, v230, v70, vcc
	v_cmp_lt_f32_e64 vcc, |v85|, s44
	s_nop 1
	v_cndmask_b32_e32 v70, v70, v85, vcc
	v_sub_f32_e32 v70, v84, v70
	v_fmac_f32_e32 v43, 0x3d800000, v70
	v_add_u32_e32 v70, 0, v45
	v_add_u32_e32 v45, 0x410, v45
	ds_write_b32 v70, v43
	s_cbranch_scc0 .LBB0_826
; __device__ __forceinline__ void phase_gla_prep(KArgs a, LAS unsigned char* lds, int tid, int wave, int lane) {
;     ...
;             __syncthreads();
;             if (hf == 1) { const float tot0 = BC[31 * BC_LD + k];
;                 for (int t = 32; t < 64; ++t) BC[t * BC_LD + k] += tot0; }
;             __syncthreads();
	s_waitcnt lgkmcnt(0)
	s_barrier
	s_and_saveexec_b64 vcc, s[6:7]
	s_cbranch_execz .LBB0_829
	ds_read_b32 v2, v46 offset:32240
	ds_read_b32 v172, v46 offset:33280
	ds_read_b32 v173, v46 offset:34320
	ds_read_b32 v174, v46 offset:35360
	ds_read_b32 v175, v46 offset:36400
	ds_read_b32 v176, v46 offset:37440
	ds_read_b32 v177, v46 offset:38480
	ds_read_b32 v194, v46 offset:39520
	ds_read_b32 v195, v46 offset:40560
	ds_read_b32 v196, v46 offset:41600
	ds_read_b32 v197, v46 offset:42640
	ds_read_b32 v198, v46 offset:43680
	ds_read_b32 v199, v46 offset:44720
	ds_read_b32 v200, v46 offset:45760
	ds_read_b32 v201, v46 offset:46800
	ds_read_b32 v202, v46 offset:47840
	ds_read_b32 v203, v46 offset:48880
	ds_read_b32 v204, v46 offset:49920
	ds_read_b32 v205, v46 offset:50960
	ds_read_b32 v206, v46 offset:52000
	ds_read_b32 v207, v46 offset:53040
	ds_read_b32 v208, v46 offset:54080
	ds_read_b32 v209, v46 offset:55120
	ds_read_b32 v210, v46 offset:56160
	ds_read_b32 v211, v46 offset:57200
	ds_read_b32 v212, v46 offset:58240
	ds_read_b32 v213, v46 offset:59280
	ds_read_b32 v214, v46 offset:60320
	ds_read_b32 v215, v46 offset:61360
	ds_read_b32 v216, v46 offset:62400
	ds_read_b32 v217, v46 offset:63440
	ds_read_b32 v232, v46 offset:64480
	ds_read_b32 v233, v46 offset:65520
	s_waitcnt lgkmcnt(0)
	v_add_f32_e32 v172, v2, v172
	ds_write_b32 v46, v172 offset:33280
	v_add_f32_e32 v173, v2, v173
	ds_write_b32 v46, v173 offset:34320
	v_add_f32_e32 v174, v2, v174
	ds_write_b32 v46, v174 offset:35360
	v_add_f32_e32 v175, v2, v175
	ds_write_b32 v46, v175 offset:36400
	v_add_f32_e32 v176, v2, v176
	ds_write_b32 v46, v176 offset:37440
	v_add_f32_e32 v177, v2, v177
	ds_write_b32 v46, v177 offset:38480
	v_add_f32_e32 v194, v2, v194
	ds_write_b32 v46, v194 offset:39520
	v_add_f32_e32 v195, v2, v195
	ds_write_b32 v46, v195 offset:40560
	v_add_f32_e32 v196, v2, v196
	ds_write_b32 v46, v196 offset:41600
	v_add_f32_e32 v197, v2, v197
	ds_write_b32 v46, v197 offset:42640
	v_add_f32_e32 v198, v2, v198
	ds_write_b32 v46, v198 offset:43680
	v_add_f32_e32 v199, v2, v199
	ds_write_b32 v46, v199 offset:44720
	v_add_f32_e32 v200, v2, v200
	ds_write_b32 v46, v200 offset:45760
	v_add_f32_e32 v201, v2, v201
	ds_write_b32 v46, v201 offset:46800
	v_add_f32_e32 v202, v2, v202
	ds_write_b32 v46, v202 offset:47840
	v_add_f32_e32 v203, v2, v203
	ds_write_b32 v46, v203 offset:48880
	v_add_f32_e32 v204, v2, v204
	ds_write_b32 v46, v204 offset:49920
	v_add_f32_e32 v205, v2, v205
	ds_write_b32 v46, v205 offset:50960
	v_add_f32_e32 v206, v2, v206
	ds_write_b32 v46, v206 offset:52000
	v_add_f32_e32 v207, v2, v207
	ds_write_b32 v46, v207 offset:53040
	v_add_f32_e32 v208, v2, v208
	ds_write_b32 v46, v208 offset:54080
	v_add_f32_e32 v209, v2, v209
	ds_write_b32 v46, v209 offset:55120
	v_add_f32_e32 v210, v2, v210
	ds_write_b32 v46, v210 offset:56160
	v_add_f32_e32 v211, v2, v211
	ds_write_b32 v46, v211 offset:57200
	v_add_f32_e32 v212, v2, v212
	ds_write_b32 v46, v212 offset:58240
	v_add_f32_e32 v213, v2, v213
	ds_write_b32 v46, v213 offset:59280
	v_add_f32_e32 v214, v2, v214
	ds_write_b32 v46, v214 offset:60320
	v_add_f32_e32 v215, v2, v215
	ds_write_b32 v46, v215 offset:61360
	v_add_f32_e32 v216, v2, v216
	ds_write_b32 v46, v216 offset:62400
	v_add_f32_e32 v217, v2, v217
	ds_write_b32 v46, v217 offset:63440
	v_add_f32_e32 v232, v2, v232
	ds_write_b32 v46, v232 offset:64480
	v_add_f32_e32 v233, v2, v233
	ds_write_b32 v46, v233 offset:65520
